# conv0 input staging: the two edge-element loads no longer wait individually (one wait per iteration instead of three)
# speedup vs baseline: 1.0061x; 1.0061x over previous
.LBB0_976:
	s_or_b64 exec, exec, s[6:7]
	s_waitcnt vmcnt(0)
	v_lshlrev_b32_e32 v13, 16, v13
	v_lshlrev_b32_e32 v12, 16, v12
	v_lshlrev_b32_e32 v4, 16, v0
	v_and_b32_e32 v0, 0xffff0000, v0
	v_mul_f32_e32 v16, v7, v0
	v_lshlrev_b32_e32 v5, 16, v1
	v_fmac_f32_e32 v16, v6, v4
	v_mul_f32_e32 v13, v6, v13
	v_fmac_f32_e32 v16, v9, v5
	v_and_b32_e32 v1, 0xffff0000, v1
	v_fmac_f32_e32 v13, v7, v4
	v_add_f32_e32 v4, v8, v16
	v_mul_f32_e32 v16, v7, v5
	v_fmac_f32_e32 v13, v9, v0
	v_fmac_f32_e32 v16, v6, v0
	v_mul_f32_e32 v0, v7, v1
	v_lshlrev_b32_e32 v14, 16, v2
	v_fmac_f32_e32 v0, v6, v5
	v_fmac_f32_e32 v0, v9, v14
	v_add_f32_e32 v5, v8, v0
	v_mul_f32_e32 v0, v7, v14
	v_and_b32_e32 v2, 0xffff0000, v2
	v_fmac_f32_e32 v0, v6, v1
	v_fmac_f32_e32 v0, v9, v2
	v_add_f32_e32 v17, v8, v0
	v_mul_f32_e32 v0, v7, v2
	v_lshlrev_b32_e32 v15, 16, v3
	v_fmac_f32_e32 v0, v6, v14
	v_fmac_f32_e32 v0, v9, v15
	v_add_f32_e32 v14, v8, v0
	v_mul_f32_e32 v0, v7, v15
	v_and_b32_e32 v3, 0xffff0000, v3
	v_fmac_f32_e32 v0, v6, v2
	v_fmac_f32_e32 v0, v9, v3
	v_add_f32_e32 v18, v8, v0
	v_mul_f32_e32 v0, v7, v3
	v_fmac_f32_e32 v0, v6, v15
	v_fmac_f32_e32 v0, v9, v12
	v_add_u32_e32 v10, 0x200, v10
	v_add_f32_e32 v13, v8, v13
	v_add_f32_e32 v3, v8, v0
	v_cvt_pk_bf16_f32 v0, v13, v4
	v_mul_lo_u32 v4, v11, s79
	v_cmp_le_i32_e64 s[36:37], s1, v10
	v_fmac_f32_e32 v16, v9, v1
	v_add3_u32 v4, s24, v4, v164
	s_or_b64 s[16:17], s[36:37], s[16:17]
	v_add_f32_e32 v16, v8, v16
	v_cvt_pk_bf16_f32 v1, v16, v5
	v_cvt_pk_bf16_f32 v2, v17, v14
	v_cvt_pk_bf16_f32 v3, v18, v3
	ds_write_b128 v4, v[0:3]
	s_andn2_b64 exec, exec, s[16:17]
	s_cbranch_execz .LBB0_981

.LBB0_979:
	s_or_b64 exec, exec, s[6:7]
	v_lshlrev_b32_e32 v14, 3, v14
	v_cmp_gt_u32_e64 s[36:37], s2, v14
	s_and_saveexec_b64 s[6:7], s[36:37]
	s_cbranch_execz .LBB0_976
	global_load_ushort v12, v[4:5], off offset:16
	s_branch .LBB0_976
